# RG-LRU background conversion stream spread over all 128 steps (9/16 of waves active per slot)
# baseline (speedup 1.0000x reference)
; #define LDS_BAR() do { asm volatile("s_waitcnt lgkmcnt(0)" ::: "memory"); __builtin_amdgcn_s_barrier(); asm volatile("" ::: "memory"); } while (0)
; #define RG_LOAD(n_) do { const long r0_ = (long)rowbase + (long)(n_) * 64; \
;         _Pragma("unroll") for (int i = 0; i < 11; ++i) xr[i] = ((n_) == 0 && 8 * rg - 3 + i < 0) ? 0u : *(const unsigned*)(xcol + (size_t)(r0_ + 8 * rg - 3 + i) * N1); } while (0)
; #define RG_LOADG(n_) do { const long r0_ = (long)rowbase + (long)(n_) * 64; \
;         _Pragma("unroll") for (int i = 0; i < 4; ++i) gbr[i] = *(const unsigned short*)(gbcol + (size_t)(r0_ + l0_ + 4 * fq + i) * N1); } while (0)
; #define RG_STAGE(xc_) do { LAS uchar* X_ = (xc_); \
;         _Pragma("unroll") for (int i = 0; i < 8; ++i) { f32x2 s2 = (f32x2){cbs[0], cbs[1]}; \
;             _Pragma("unroll") for (int k = 0; k < 4; ++k) s2 += (f32x2){cw[k][0], cw[k][1]} * (f32x2){bflo(xr[i + k]), bfhi(xr[i + k])}; \
;             *(LAS unsigned*)(X_ + (8 * rg + i) * S128 + c2 * 4) = pk2(s2.x, s2.y); } } while (0)
; DI void rglru_scan_unit(Frame& F, const Mix0Args& a, int u) {
;     ...
;     RG_LOAD(0);
;     RG_STAGE(XC0);
;     unsigned gb_cur[4];
;     RG_LOAD(1); RG_LOADG(0);
;     LDS_BAR();
;     const int nsl = cv_on ? min(NCH / 4, max(0, (CV_NIT - 8 * F.vcu + NGW - 1) / NGW)) : 0;
.LBB0_244:
	s_or_b64 exec, exec, s[8:9]
	v_or_b32_e32 v6, s82, v86
	v_mad_u64_u32 v[6:7], s[8:9], v6, s33, v[2:3]
	v_mad_i32_i24 v7, s83, v159, v7
	global_load_dword v13, v[6:7], off
	s_mov_b64 s[100:101], 0x30000
	v_lshl_add_u64 v[6:7], v[4:5], 0, s[100:101]
	s_mov_b32 s36, 0x60000
	global_load_dword v16, v[6:7], off
	s_mov_b64 s[100:101], 0x3c000
	v_lshl_add_u64 v[6:7], v[4:5], 0, s[100:101]
	s_waitcnt vmcnt(2)
	v_lshlrev_b32_e32 v14, 16, v12
	global_load_dword v17, v[6:7], off
	s_mov_b64 s[100:101], 0x48000
	v_lshl_add_u64 v[6:7], v[4:5], 0, s[100:101]
	v_and_b32_e32 v15, 0xffff0000, v12
	global_load_dword v18, v[6:7], off
	s_mov_b64 s[100:101], 0x54000
	v_lshl_add_u64 v[6:7], v[4:5], 0, s[100:101]
	v_lshlrev_b32_e32 v112, 1, v9
	global_load_dword v19, v[6:7], off
	v_add_co_u32_e32 v6, vcc, s36, v4
	v_readlane_b32 s8, v253, 55
	s_nop 0
	v_addc_co_u32_e32 v7, vcc, 0, v5, vcc
	global_load_dword v20, v[6:7], off
	s_mov_b64 s[100:101], 0x6c000
	v_lshl_add_u64 v[6:7], v[4:5], 0, s[100:101]
	v_mov_b32_e32 v113, v83
	global_load_dword v21, v[6:7], off
	s_mov_b64 s[100:101], 0x78000
	v_lshl_add_u64 v[4:5], v[4:5], 0, s[100:101]
	v_readlane_b32 s9, v253, 56
	global_load_dword v22, v[4:5], off
	v_lshlrev_b32_e32 v6, 16, v10
	v_and_b32_e32 v7, 0xffff0000, v10
	v_pk_fma_f32 v[6:7], v[104:105], v[6:7], v[100:101]
	v_lshlrev_b32_e32 v10, 16, v11
	v_and_b32_e32 v11, 0xffff0000, v11
	v_pk_fma_f32 v[6:7], v[106:107], v[10:11], v[6:7]
	v_lshl_add_u64 v[4:5], s[8:9], 0, v[112:113]
	v_pk_fma_f32 v[6:7], v[108:109], v[14:15], v[6:7]
	v_readlane_b32 s3, v253, 2
	s_cmp_lg_u32 s92, s3
	s_mov_b32 s3, 0x18000
	s_cselect_b64 s[40:41], -1, 0
	s_mov_b32 s93, 0
	v_writelane_b32 v252, s40, 4
	s_waitcnt vmcnt(7)
	v_lshlrev_b32_e32 v12, 16, v13
	v_and_b32_e32 v13, 0xffff0000, v13
	v_pk_fma_f32 v[6:7], v[110:111], v[12:13], v[6:7]
	v_writelane_b32 v252, s41, 5
	v_cvt_pk_bf16_f32 v9, v6, v7
	v_pk_fma_f32 v[6:7], v[104:105], v[10:11], v[100:101]
	s_waitcnt vmcnt(6)
	v_lshlrev_b32_e32 v10, 16, v16
	v_pk_fma_f32 v[6:7], v[106:107], v[14:15], v[6:7]
	v_and_b32_e32 v11, 0xffff0000, v16
	v_pk_fma_f32 v[6:7], v[108:109], v[12:13], v[6:7]
	v_add_u32_e32 v16, 0x400, v156
	v_pk_fma_f32 v[6:7], v[110:111], v[10:11], v[6:7]
	s_nop 0
	v_cvt_pk_bf16_f32 v6, v6, v7
	ds_write2_b32 v156, v9, v6 offset1:72
	v_pk_fma_f32 v[6:7], v[104:105], v[14:15], v[100:101]
	s_waitcnt vmcnt(5)
	v_lshlrev_b32_e32 v14, 16, v17
	v_pk_fma_f32 v[6:7], v[106:107], v[12:13], v[6:7]
	v_and_b32_e32 v15, 0xffff0000, v17
	v_pk_fma_f32 v[6:7], v[108:109], v[10:11], v[6:7]
	s_nop 0
	v_pk_fma_f32 v[6:7], v[110:111], v[14:15], v[6:7]
	s_nop 0
	v_cvt_pk_bf16_f32 v9, v6, v7
	v_pk_fma_f32 v[6:7], v[104:105], v[12:13], v[100:101]
	s_waitcnt vmcnt(4)
	v_lshlrev_b32_e32 v12, 16, v18
	v_pk_fma_f32 v[6:7], v[106:107], v[10:11], v[6:7]
	v_and_b32_e32 v13, 0xffff0000, v18
	v_pk_fma_f32 v[6:7], v[108:109], v[14:15], v[6:7]
	s_nop 0
	v_pk_fma_f32 v[6:7], v[110:111], v[12:13], v[6:7]
	s_nop 0
	v_cvt_pk_bf16_f32 v6, v6, v7
	ds_write2_b32 v156, v9, v6 offset0:144 offset1:216
	v_pk_fma_f32 v[6:7], v[104:105], v[10:11], v[100:101]
	s_waitcnt vmcnt(3)
	v_lshlrev_b32_e32 v10, 16, v19
	v_pk_fma_f32 v[6:7], v[106:107], v[14:15], v[6:7]
	v_and_b32_e32 v11, 0xffff0000, v19
	v_pk_fma_f32 v[6:7], v[108:109], v[12:13], v[6:7]
	s_nop 0
	v_pk_fma_f32 v[6:7], v[110:111], v[10:11], v[6:7]
	s_nop 0
	v_cvt_pk_bf16_f32 v9, v6, v7
	v_pk_fma_f32 v[6:7], v[104:105], v[14:15], v[100:101]
	s_waitcnt vmcnt(2)
	v_lshlrev_b32_e32 v14, 16, v20
	v_pk_fma_f32 v[6:7], v[106:107], v[12:13], v[6:7]
	v_and_b32_e32 v15, 0xffff0000, v20
	v_pk_fma_f32 v[6:7], v[108:109], v[10:11], v[6:7]
	s_nop 0
	v_pk_fma_f32 v[6:7], v[110:111], v[14:15], v[6:7]
	s_nop 0
	v_cvt_pk_bf16_f32 v6, v6, v7
	ds_write2_b32 v16, v9, v6 offset0:32 offset1:104
	v_pk_fma_f32 v[6:7], v[104:105], v[12:13], v[100:101]
	s_waitcnt vmcnt(1)
	v_lshlrev_b32_e32 v12, 16, v21
	v_pk_fma_f32 v[6:7], v[106:107], v[10:11], v[6:7]
	v_and_b32_e32 v13, 0xffff0000, v21
	v_pk_fma_f32 v[6:7], v[108:109], v[14:15], v[6:7]
	s_nop 0
	v_pk_fma_f32 v[6:7], v[110:111], v[12:13], v[6:7]
	s_nop 0
	v_cvt_pk_bf16_f32 v9, v6, v7
	v_pk_fma_f32 v[6:7], v[104:105], v[10:11], v[100:101]
	s_waitcnt vmcnt(0)
	v_lshlrev_b32_e32 v10, 16, v22
	v_pk_fma_f32 v[6:7], v[106:107], v[14:15], v[6:7]
	v_and_b32_e32 v11, 0xffff0000, v22
	v_pk_fma_f32 v[6:7], v[108:109], v[12:13], v[6:7]
	s_nop 0
	v_pk_fma_f32 v[6:7], v[110:111], v[10:11], v[6:7]
	s_nop 0
	v_cvt_pk_bf16_f32 v6, v6, v7
	ds_write2_b32 v16, v9, v6 offset0:176 offset1:248
	v_or_b32_e32 v6, s82, v88
	v_mad_u64_u32 v[2:3], s[8:9], v6, s33, v[2:3]
	v_mad_i32_i24 v3, s83, v159, v3
	v_add_co_u32_e32 v6, vcc, s33, v2
	global_load_dword v130, v[2:3], off
	s_nop 0
	v_addc_co_u32_e32 v7, vcc, 0, v3, vcc
	global_load_dword v132, v[6:7], off
	v_add_co_u32_e32 v6, vcc, s3, v2
	s_mov_b32 s3, 0x24000
	s_nop 0
	v_addc_co_u32_e32 v7, vcc, 0, v3, vcc
	global_load_dword v134, v[6:7], off
	v_add_co_u32_e32 v6, vcc, s3, v2
	s_mov_b32 s3, 0x30000
	s_nop 0
	v_addc_co_u32_e32 v7, vcc, 0, v3, vcc
	global_load_dword v169, v[6:7], off
	v_add_co_u32_e32 v6, vcc, s3, v2
	s_mov_b32 s3, 0x3c000
	s_nop 0
	v_addc_co_u32_e32 v7, vcc, 0, v3, vcc
	global_load_dword v170, v[6:7], off
	v_add_co_u32_e32 v6, vcc, s3, v2
	s_mov_b32 s3, 0x48000
	s_nop 0
	v_addc_co_u32_e32 v7, vcc, 0, v3, vcc
	global_load_dword v171, v[6:7], off
	v_add_co_u32_e32 v6, vcc, s3, v2
	s_mov_b32 s3, 0x54000
	s_nop 0
	v_addc_co_u32_e32 v7, vcc, 0, v3, vcc
	global_load_dword v172, v[6:7], off
	v_add_co_u32_e32 v6, vcc, s3, v2
	s_mov_b32 s3, 0x6c000
	s_nop 0
	v_addc_co_u32_e32 v7, vcc, 0, v3, vcc
	global_load_dword v173, v[6:7], off
	v_add_co_u32_e32 v6, vcc, s36, v2
	s_nop 1
	v_addc_co_u32_e32 v7, vcc, 0, v3, vcc
	global_load_dword v174, v[6:7], off
	v_add_co_u32_e32 v6, vcc, s3, v2
	s_mov_b32 s3, 0x78000
	s_nop 0
	v_addc_co_u32_e32 v7, vcc, 0, v3, vcc
	v_add_co_u32_e32 v2, vcc, s3, v2
	global_load_dword v175, v[6:7], off
	s_nop 0
	v_addc_co_u32_e32 v3, vcc, 0, v3, vcc
	global_load_dword v176, v[2:3], off
	v_or_b32_e32 v2, s82, v90
	v_mad_u64_u32 v[6:7], s[8:9], v2, s33, v[4:5]
	v_mad_i32_i24 v7, s83, v159, v7
	v_add_co_u32_e32 v4, vcc, s33, v6
	global_load_ushort v2, v[6:7], off
	s_nop 0
	v_addc_co_u32_e32 v5, vcc, 0, v7, vcc
	global_load_ushort v3, v[4:5], off
	s_mov_b64 s[100:101], 0x18000
	v_lshl_add_u64 v[4:5], v[6:7], 0, s[100:101]
	s_mov_b32 s3, 0
	s_mov_b64 s[100:101], 0x24000
	v_lshl_add_u64 v[6:7], v[6:7], 0, s[100:101]
	global_load_ushort v4, v[4:5], off
	global_load_ushort v5, v[6:7], off
	s_waitcnt lgkmcnt(0)
	s_barrier
	s_and_b64 vcc, exec, s[40:41]
	s_cbranch_vccnz .LBB0_246
	s_mov_b32 s3, 32

; #define LAS __attribute__((address_space(3)))
; #define RG_STAGE(xc_) do { LAS uchar* X_ = (xc_); \
;         _Pragma("unroll") for (int i = 0; i < 8; ++i) { f32x2 s2 = (f32x2){cbs[0], cbs[1]}; \
;             _Pragma("unroll") for (int k = 0; k < 4; ++k) s2 += (f32x2){cw[k][0], cw[k][1]} * (f32x2){bflo(xr[i + k]), bfhi(xr[i + k])}; \
;             *(LAS unsigned*)(X_ + (8 * rg + i) * S128 + c2 * 4) = pk2(s2.x, s2.y); } } while (0)
; DI void rglru_scan_unit(Frame& F, const Mix0Args& a, int u) {
;     ...
;         LAS uchar* XCc = XC0 + (n & 1) * 64 * S128; LAS uchar* XCn = XC0 + ((n + 1) & 1) * 64 * S128;
;         LAS float* SEGA = SEG0 + (n & 1) * 1280; LAS float* SEGH = SEGA + 640;
; #pragma unroll
;         for (int i = 0; i < 4; ++i) gb_cur[i] = gbr[i];
;         if (n + 1 < NCH) RG_STAGE(XCn);
;         if constexpr (CQ == 0) { if (n > 0) { const int ip = ((n >> 2) - 1) * NGW + gw; if (ip < CV_NIT) cv_finish(a.cv, ip, lane, cq0, cq1, cq2, cq3, CVS); } }
.LBB0_249:
	v_lshlrev_b32_e32 v66, 16, v130
	v_and_b32_e32 v67, 0xffff0000, v130
	v_pk_fma_f32 v[66:67], v[104:105], v[66:67], v[100:101]
	v_lshlrev_b32_e32 v68, 16, v132
	v_and_b32_e32 v69, 0xffff0000, v132
	v_pk_fma_f32 v[66:67], v[106:107], v[68:69], v[66:67]
	v_lshlrev_b32_e32 v70, 16, v134
	v_and_b32_e32 v71, 0xffff0000, v134
	v_pk_fma_f32 v[66:67], v[108:109], v[70:71], v[66:67]
	s_waitcnt vmcnt(15)
	v_lshlrev_b32_e32 v72, 16, v169
	v_and_b32_e32 v73, 0xffff0000, v169
	v_pk_fma_f32 v[66:67], v[110:111], v[72:73], v[66:67]
	v_add_u32_e32 v183, 0x4800, v123
	v_cvt_pk_bf16_f32 v74, v66, v67
	v_pk_fma_f32 v[66:67], v[104:105], v[68:69], v[100:101]
	s_waitcnt vmcnt(14)
	v_lshlrev_b32_e32 v68, 16, v170
	v_pk_fma_f32 v[66:67], v[106:107], v[70:71], v[66:67]
	v_and_b32_e32 v69, 0xffff0000, v170
	v_pk_fma_f32 v[66:67], v[108:109], v[72:73], v[66:67]
	v_add_u32_e32 v182, 0x4c00, v123
	v_pk_fma_f32 v[66:67], v[110:111], v[68:69], v[66:67]
	s_cmp_eq_u32 s8, 0
	v_cvt_pk_bf16_f32 v66, v66, v67
	ds_write2_b32 v183, v74, v66 offset1:72
	v_pk_fma_f32 v[66:67], v[104:105], v[70:71], v[100:101]
	s_waitcnt vmcnt(13)
	v_lshlrev_b32_e32 v70, 16, v171
	v_pk_fma_f32 v[66:67], v[106:107], v[72:73], v[66:67]
	v_and_b32_e32 v71, 0xffff0000, v171
	v_pk_fma_f32 v[66:67], v[108:109], v[68:69], v[66:67]
	s_mov_b32 s36, 0
	v_pk_fma_f32 v[66:67], v[110:111], v[70:71], v[66:67]
	s_nop 0
	v_cvt_pk_bf16_f32 v74, v66, v67
	v_pk_fma_f32 v[66:67], v[104:105], v[72:73], v[100:101]
	s_waitcnt vmcnt(12)
	v_lshlrev_b32_e32 v72, 16, v172
	v_pk_fma_f32 v[66:67], v[106:107], v[68:69], v[66:67]
	v_and_b32_e32 v73, 0xffff0000, v172
	v_pk_fma_f32 v[66:67], v[108:109], v[70:71], v[66:67]
	s_nop 0
	v_pk_fma_f32 v[66:67], v[110:111], v[72:73], v[66:67]
	s_nop 0
	v_cvt_pk_bf16_f32 v66, v66, v67
	ds_write2_b32 v183, v74, v66 offset0:144 offset1:216
	v_pk_fma_f32 v[66:67], v[104:105], v[68:69], v[100:101]
	s_waitcnt vmcnt(11)
	v_lshlrev_b32_e32 v68, 16, v173
	v_pk_fma_f32 v[66:67], v[106:107], v[70:71], v[66:67]
	v_and_b32_e32 v69, 0xffff0000, v173
	v_pk_fma_f32 v[66:67], v[108:109], v[72:73], v[66:67]
	s_nop 0
	v_pk_fma_f32 v[66:67], v[110:111], v[68:69], v[66:67]
	s_nop 0
	v_cvt_pk_bf16_f32 v74, v66, v67
	v_pk_fma_f32 v[66:67], v[104:105], v[70:71], v[100:101]
	s_waitcnt vmcnt(10)
	v_lshlrev_b32_e32 v70, 16, v174
	v_pk_fma_f32 v[66:67], v[106:107], v[72:73], v[66:67]
	v_and_b32_e32 v71, 0xffff0000, v174
	v_pk_fma_f32 v[66:67], v[108:109], v[68:69], v[66:67]
	s_nop 0
	v_pk_fma_f32 v[66:67], v[110:111], v[70:71], v[66:67]
	s_nop 0
	v_cvt_pk_bf16_f32 v66, v66, v67
	ds_write2_b32 v182, v74, v66 offset0:32 offset1:104
	v_pk_fma_f32 v[66:67], v[104:105], v[72:73], v[100:101]
	s_waitcnt vmcnt(9)
	v_lshlrev_b32_e32 v72, 16, v175
	v_pk_fma_f32 v[66:67], v[106:107], v[68:69], v[66:67]
	v_and_b32_e32 v73, 0xffff0000, v175
	v_pk_fma_f32 v[66:67], v[108:109], v[70:71], v[66:67]
	s_nop 0
	v_pk_fma_f32 v[66:67], v[110:111], v[72:73], v[66:67]
	s_nop 0
	v_cvt_pk_bf16_f32 v74, v66, v67
	v_pk_fma_f32 v[66:67], v[104:105], v[68:69], v[100:101]
	s_waitcnt vmcnt(8)
	v_lshlrev_b32_e32 v68, 16, v176
	v_pk_fma_f32 v[66:67], v[106:107], v[70:71], v[66:67]
	v_and_b32_e32 v69, 0xffff0000, v176
	v_pk_fma_f32 v[66:67], v[108:109], v[72:73], v[66:67]
	s_nop 0
	v_pk_fma_f32 v[66:67], v[110:111], v[68:69], v[66:67]
	s_nop 0
	v_cvt_pk_bf16_f32 v66, v66, v67
	ds_write2_b32 v182, v74, v66 offset0:176 offset1:248
	s_cbranch_scc1 .LBB0_263
	s_add_i32 s36, s77, -1
	s_mul_i32 s37, s36, 7
	s_add_i32 s37, s37, s95
	s_add_i32 s84, s94, -1
	s_and_b32 s37, s37, s84
	s_mul_i32 s36, s36, s94
	s_add_i32 s36, s36, s37
	s_mul_i32 s36, s36, 9
	s_and_b32 s37, s36, 15
	s_lshr_b32 s86, s36, 4
	s_cmp_lt_u32 s37, 9
	s_cselect_b32 s86, s86, 0x10000
	s_cmp_gt_i32 s86, 0x887f
	s_mov_b32 s36, s77
	s_cbranch_scc1 .LBB0_263
	s_mov_b32 s84, s86
	s_cmpk_lt_i32 s86, 0x2000
	s_cbranch_scc1 .LBB0_256
	s_cmpk_gt_u32 s86, 0x687f
	s_mov_b64 s[36:37], -1
	s_cbranch_scc0 .LBB0_254
	s_add_i32 s88, s86, 0xffff9780
	s_mov_b64 s[36:37], 0
	s_mov_b64 s[78:79], s[50:51]

; #define RG_LOAD(n_) do { const long r0_ = (long)rowbase + (long)(n_) * 64; \
;         _Pragma("unroll") for (int i = 0; i < 11; ++i) xr[i] = ((n_) == 0 && 8 * rg - 3 + i < 0) ? 0u : *(const unsigned*)(xcol + (size_t)(r0_ + 8 * rg - 3 + i) * N1); } while (0)
; #define RG_LOADG(n_) do { const long r0_ = (long)rowbase + (long)(n_) * 64; \
;         _Pragma("unroll") for (int i = 0; i < 4; ++i) gbr[i] = *(const unsigned short*)(gbcol + (size_t)(r0_ + l0_ + 4 * fq + i) * N1); } while (0)
; DI void rglru_scan_unit(Frame& F, const Mix0Args& a, int u) {
;     ...
;         if (n + 2 < NCH) RG_LOAD(n + 2);
;         if (n + 1 < NCH) RG_LOADG(n + 1);
;         if constexpr (CV) { int idx = (n >> 2) * NGW + gw; idx = idx < CV_NIT ? idx : idx - CV_NIT;
;             if constexpr (CQ == 0) cv_issue_q(a.cv, idx, lane, cq0, 0); else if constexpr (CQ == 1) cv_issue_q(a.cv, idx, lane, cq1, 4); else if constexpr (CQ == 2) cv_issue_q(a.cv, idx, lane, cq2, 8); else cv_issue_q(a.cv, idx, lane, cq3, 12); }
.LBB0_263:
	s_waitcnt vmcnt(4)
	v_lshl_add_u64 v[50:51], v[120:121], 0, s[8:9]
	s_mov_b64 s[100:101], 0x258e4000
	v_lshl_add_u64 v[2:3], v[50:51], 0, s[100:101]
	v_lshl_add_u64 v[52:53], v[118:119], 0, s[8:9]
	global_load_dword v18, v[2:3], off
	s_mov_b64 s[100:101], 0x258f0000
	v_lshl_add_u64 v[2:3], v[50:51], 0, s[100:101]
	s_mul_i32 s37, s36, 7
	s_add_i32 s37, s37, s95
	s_add_i32 s40, s94, -1
	s_and_b32 s37, s37, s40
	s_mul_i32 s36, s36, s94
	s_add_i32 s36, s36, s37
	s_mul_i32 s36, s36, 9
	s_and_b32 s37, s36, 15
	s_lshr_b32 s36, s36, 4
	s_and_b32 s40, s95, 63
	s_add_i32 s40, s40, 0x8880
	s_cmp_lt_u32 s37, 9
	s_cselect_b32 s36, s36, s40
	s_cmp_lt_u32 s36, 0x8880
	s_cselect_b32 s36, s36, s40
	global_load_dword v19, v[2:3], off
	s_mov_b64 s[100:101], 0x258fc000
	v_lshl_add_u64 v[2:3], v[50:51], 0, s[100:101]
	global_load_dword v20, v[2:3], off
	s_mov_b64 s[100:101], 0x25908000
	v_lshl_add_u64 v[2:3], v[50:51], 0, s[100:101]
	s_add_i32 s37, s36, 0xffff7780
	global_load_dword v21, v[2:3], off
	s_mov_b64 s[100:101], 0x25914000
	v_lshl_add_u64 v[2:3], v[50:51], 0, s[100:101]
	s_cmp_lt_i32 s36, 0x8880
	global_load_dword v22, v[2:3], off
	s_mov_b64 s[100:101], 0x25920000
	v_lshl_add_u64 v[2:3], v[50:51], 0, s[100:101]
	s_cselect_b32 s87, s36, s37
	global_load_dword v23, v[2:3], off
	s_mov_b64 s[100:101], 0x2592c000
	v_lshl_add_u64 v[2:3], v[50:51], 0, s[100:101]
	s_cmpk_gt_i32 s87, 0x1fff
	global_load_dword v24, v[2:3], off
	s_mov_b64 s[100:101], 0x25938000
	v_lshl_add_u64 v[2:3], v[50:51], 0, s[100:101]
	s_cselect_b64 s[40:41], -1, 0
	global_load_dword v27, v[2:3], off
	s_mov_b64 s[100:101], 0x25944000
	v_lshl_add_u64 v[2:3], v[50:51], 0, s[100:101]
	s_cmpk_lt_i32 s87, 0x2000
	global_load_dword v25, v[2:3], off
	s_mov_b64 s[100:101], 0x25950000
	v_lshl_add_u64 v[2:3], v[50:51], 0, s[100:101]
	global_load_dword v26, v[2:3], off
	s_mov_b64 s[100:101], 0x2595c000
	v_lshl_add_u64 v[2:3], v[50:51], 0, s[100:101]
	global_load_dword v28, v[2:3], off
	s_mov_b64 s[100:101], 0x2560a000
	v_lshl_add_u64 v[2:3], v[52:53], 0, s[100:101]
	global_load_ushort v37, v[2:3], off
	s_mov_b64 s[100:101], 0x25616000
	v_lshl_add_u64 v[2:3], v[52:53], 0, s[100:101]
	global_load_ushort v36, v[2:3], off
	s_mov_b64 s[100:101], 0x25622000
	v_lshl_add_u64 v[2:3], v[52:53], 0, s[100:101]
	global_load_ushort v34, v[2:3], off
	s_mov_b64 s[100:101], 0x2562e000
	v_lshl_add_u64 v[2:3], v[52:53], 0, s[100:101]
	global_load_ushort v35, v[2:3], off
	s_cbranch_scc1 .LBB0_266
	s_cmpk_gt_u32 s87, 0x687f
	s_cbranch_scc0 .LBB0_267
	s_add_i32 s84, s87, 0xffff9780
	s_mov_b64 s[36:37], s[52:53]
	s_movk_i32 s78, 0x1000
	s_cbranch_execz .LBB0_268
	s_branch .LBB0_269

; DI void cv_decode(const CvJob& j, int idx, const float*& W, int& K, int& N, bf16*& WT, const float*& ks, int& item) {
;     if (idx < CV_I2) { W = j.e_w_out; K = K2; N = D; WT = j.W2; ks = nullptr; item = idx; }
;     else if (idx < CV_I2 + CV_I3) { W = j.o_w_in; K = D; N = N3; WT = j.W3; ks = j.kscale3; item = idx - CV_I2; }
;     else { W = j.o_w_out; K = K4; N = D; WT = j.W4; ks = j.kscale4; item = idx - CV_I2 - CV_I3; }
; DI void rglru_scan_unit(Frame& F, const Mix0Args& a, int u) {
;     ...
;         if constexpr (CQ == 0) { if (n > 0) { const int ip = ((n >> 2) - 1) * NGW + gw; if (ip < CV_NIT) cv_finish(a.cv, ip, lane, cq0, cq1, cq2, cq3, CVS); } }
.LBB0_305:
	v_readlane_b32 s8, v252, 6
	v_readlane_b32 s9, v252, 7
	s_andn2_b64 vcc, exec, s[8:9]
	s_cbranch_vccnz .LBB0_319
	s_add_i32 s3, s3, -1
	s_mul_i32 s8, s3, 7
	s_add_i32 s8, s8, s95
	s_add_i32 s9, s94, -1
	s_and_b32 s8, s8, s9
	s_mul_i32 s3, s3, s94
	s_add_i32 s3, s3, s8
	s_mul_i32 s3, s3, 9
	s_and_b32 s8, s3, 15
	s_lshr_b32 s3, s3, 4
	s_cmp_lt_u32 s8, 9
	s_cselect_b32 s3, s3, 0x10000
	s_cmp_gt_i32 s3, 0x887f
	s_cbranch_scc1 .LBB0_319
	s_cmpk_lt_i32 s3, 0x2000
	s_cbranch_scc1 .LBB0_312
	s_cmpk_gt_u32 s3, 0x687f
	s_mov_b64 s[8:9], -1
	s_cbranch_scc0 .LBB0_310
	s_add_i32 s40, s3, 0xffff9780
	s_mov_b64 s[8:9], 0
	s_mov_b64 s[78:79], s[50:51]
